# MLA loop: LDS-DMA pieces of tile j+2 issued between the last P.V MFMAs instead of in a burst before the barrier (on top of the P.V / softmax interleave)
# baseline (speedup 1.0000x reference)
; #define ATT_SBAR() __builtin_amdgcn_sched_barrier(0)
; template <int OFF> __device__ __forceinline__ s16x4 tr_read(int vb) { s16x4 r; asm volatile("ds_read_b64_tr_b16 %0, %1 offset:%2" : "=&v"(r) : "v"(vb), "i"(OFF) : "memory"); return r; }
; template <int D0> __device__ __forceinline__ void pv_read(VFrag& f, int vb) {
;   f.l0 = tr_read<v_rd_off(D0, 0, 0)>(vb); f.h0 = tr_read<v_rd_off(D0, 0, 1)>(vb); f.l1 = tr_read<v_rd_off(D0, 1, 0)>(vb); f.h1 = tr_read<v_rd_off(D0, 1, 1)>(vb);
;   f.l2 = tr_read<v_rd_off(D0, 2, 0)>(vb); f.h2 = tr_read<v_rd_off(D0, 2, 1)>(vb); f.l3 = tr_read<v_rd_off(D0, 3, 0)>(vb); f.h3 = tr_read<v_rd_off(D0, 3, 1)>(vb);
; }
; __device__ __forceinline__ void pv_mma(f32x16& od, const VFrag& f, bf16x8 pa0, bf16x8 pa1, bf16x8 pa2, bf16x8 pa3) {
;     ...
;   od = __builtin_amdgcn_mfma_f32_32x32x16_bf16(pa0, ATT_PK(f.l0, f.h0), od, 0, 0, 0);
;   od = __builtin_amdgcn_mfma_f32_32x32x16_bf16(pa1, ATT_PK(f.l1, f.h1), od, 0, 0, 0);
;   od = __builtin_amdgcn_mfma_f32_32x32x16_bf16(pa2, ATT_PK(f.l2, f.h2), od, 0, 0, 0);
;   od = __builtin_amdgcn_mfma_f32_32x32x16_bf16(pa3, ATT_PK(f.l3, f.h3), od, 0, 0, 0);
;     ...
; }
; __device__ __forceinline__ void pv_d0(f32x16* o, int vb, bf16x8 pa0, bf16x8 pa1, bf16x8 pa2, bf16x8 pa3) {
;   VFrag fa, fb;
;   pv_read<0>(fa, vb); pv_read<1>(fb, vb);
;   asm volatile("s_waitcnt lgkmcnt(8)" ::: "memory"); ATT_SBAR(); pv_mma(o[0], fa, pa0, pa1, pa2, pa3); ATT_SBAR();
;   pv_read<2>(fa, vb);
;   asm volatile("s_waitcnt lgkmcnt(8)" ::: "memory"); ATT_SBAR(); pv_mma(o[1], fb, pa0, pa1, pa2, pa3); ATT_SBAR();
;   pv_read<3>(fb, vb);
;   asm volatile("s_waitcnt lgkmcnt(8)" ::: "memory"); ATT_SBAR(); pv_mma(o[2], fa, pa0, pa1, pa2, pa3); ATT_SBAR();
;   asm volatile("s_waitcnt lgkmcnt(0)" ::: "memory"); ATT_SBAR(); pv_mma(o[3], fb, pa0, pa1, pa2, pa3);
; template <int MODE>
; __device__ __forceinline__ void attn_unit(unsigned char* ws_, const float* rpb, const float* sink, int l, int h, int qb, int kvq, unsigned char* lds_g) {
;     ...
;     ATT_SBAR();
;     if (j + 2 < T1) ATT_DMA(j + 2, bn);
;     if (j + 2 < T1) asm volatile("s_waitcnt vmcnt(%0)" :: "n"(NCH + 2) : "memory"); else asm volatile("s_waitcnt vmcnt(0)" ::: "memory");
.Lmla_nors:
	v_lshl_add_u32 v230, s10, 14, v200
	ds_read_b64_tr_b16 v[160:161], v230 offset:0
	ds_read_b64_tr_b16 v[162:163], v230 offset:2048
	ds_read_b64_tr_b16 v[164:165], v230 offset:512
	ds_read_b64_tr_b16 v[166:167], v230 offset:2560
	ds_read_b64_tr_b16 v[168:169], v230 offset:1024
	ds_read_b64_tr_b16 v[170:171], v230 offset:3072
	ds_read_b64_tr_b16 v[172:173], v230 offset:1536
	ds_read_b64_tr_b16 v[174:175], v230 offset:3584
	v_mov_b32_e32 v252, 0
	v_mov_b32_e32 v253, 0
	v_fma_f32 v82, v82, s56, -v148
	v_exp_f32_e32 v82, v82
	v_fma_f32 v83, v83, s56, -v148
	v_exp_f32_e32 v83, v83
	v_fma_f32 v84, v84, s56, -v148
	v_exp_f32_e32 v84, v84
	v_fma_f32 v85, v85, s56, -v148
	v_exp_f32_e32 v85, v85
	v_fma_f32 v86, v86, s56, -v148
	v_exp_f32_e32 v86, v86
	v_fma_f32 v87, v87, s56, -v148
	v_exp_f32_e32 v87, v87
	v_fma_f32 v88, v88, s56, -v148
	v_exp_f32_e32 v88, v88
	v_fma_f32 v89, v89, s56, -v148
	v_exp_f32_e32 v89, v89
	v_add_f32_e32 v252, v252, v82
	v_add_f32_e32 v253, v253, v83
	v_add_f32_e32 v252, v252, v84
	v_add_f32_e32 v253, v253, v85
	v_cvt_pk_bf16_f32 v204, v82, v83
	v_cvt_pk_bf16_f32 v205, v84, v85
	v_add_f32_e32 v252, v252, v86
	v_add_f32_e32 v253, v253, v87
	v_add_f32_e32 v252, v252, v88
	v_add_f32_e32 v253, v253, v89
	v_cvt_pk_bf16_f32 v206, v86, v87
	v_cvt_pk_bf16_f32 v207, v88, v89
	ds_read_b64_tr_b16 v[240:241], v230 offset:4096
	ds_read_b64_tr_b16 v[242:243], v230 offset:6144
	ds_read_b64_tr_b16 v[244:245], v230 offset:4608
	ds_read_b64_tr_b16 v[246:247], v230 offset:6656
	ds_read_b64_tr_b16 v[248:249], v230 offset:5120
	ds_read_b64_tr_b16 v[250:251], v230 offset:7168
	ds_read_b64_tr_b16 v[84:85], v230 offset:5632
	ds_read_b64_tr_b16 v[86:87], v230 offset:7680
	s_waitcnt lgkmcnt(8)
	v_mfma_f32_32x32x16_bf16 v[2:17], v[204:207], v[160:163], v[2:17]
	v_fma_f32 v90, v90, s56, -v148
	v_exp_f32_e32 v90, v90
	v_fma_f32 v91, v91, s56, -v148
	v_exp_f32_e32 v91, v91
	v_fma_f32 v92, v92, s56, -v148
	v_exp_f32_e32 v92, v92
	v_fma_f32 v93, v93, s56, -v148
	v_exp_f32_e32 v93, v93
	v_mfma_f32_32x32x16_bf16 v[50:65], v[204:207], v[164:167], v[50:65]
	v_fma_f32 v94, v94, s56, -v148
	v_exp_f32_e32 v94, v94
	v_fma_f32 v95, v95, s56, -v148
	v_exp_f32_e32 v95, v95
	v_fma_f32 v96, v96, s56, -v148
	v_exp_f32_e32 v96, v96
	v_fma_f32 v97, v97, s56, -v148
	v_exp_f32_e32 v97, v97
	v_mfma_f32_32x32x16_bf16 v[34:49], v[204:207], v[168:171], v[34:49]
	v_add_f32_e32 v252, v252, v90
	v_add_f32_e32 v253, v253, v91
	v_add_f32_e32 v252, v252, v92
	v_add_f32_e32 v253, v253, v93
	v_cvt_pk_bf16_f32 v208, v90, v91
	v_cvt_pk_bf16_f32 v209, v92, v93
	v_add_f32_e32 v252, v252, v94
	v_mfma_f32_32x32x16_bf16 v[18:33], v[204:207], v[172:175], v[18:33]
	v_add_f32_e32 v253, v253, v95
	v_add_f32_e32 v252, v252, v96
	v_add_f32_e32 v253, v253, v97
	v_cvt_pk_bf16_f32 v210, v94, v95
	v_cvt_pk_bf16_f32 v211, v96, v97
	ds_read_b64_tr_b16 v[160:161], v230 offset:8192
	ds_read_b64_tr_b16 v[162:163], v230 offset:10240
	ds_read_b64_tr_b16 v[164:165], v230 offset:8704
	ds_read_b64_tr_b16 v[166:167], v230 offset:10752
	ds_read_b64_tr_b16 v[168:169], v230 offset:9216
	ds_read_b64_tr_b16 v[170:171], v230 offset:11264
	ds_read_b64_tr_b16 v[172:173], v230 offset:9728
	ds_read_b64_tr_b16 v[174:175], v230 offset:11776
	s_waitcnt lgkmcnt(8)
	v_mfma_f32_32x32x16_bf16 v[2:17], v[208:211], v[240:243], v[2:17]
	v_fma_f32 v66, v66, s56, -v148
	v_exp_f32_e32 v66, v66
	v_fma_f32 v67, v67, s56, -v148
	v_exp_f32_e32 v67, v67
	v_fma_f32 v68, v68, s56, -v148
	v_exp_f32_e32 v68, v68
	v_fma_f32 v69, v69, s56, -v148
	v_exp_f32_e32 v69, v69
	v_mfma_f32_32x32x16_bf16 v[50:65], v[208:211], v[244:247], v[50:65]
	v_fma_f32 v70, v70, s56, -v148
	v_exp_f32_e32 v70, v70
	v_fma_f32 v71, v71, s56, -v148
	v_exp_f32_e32 v71, v71
	v_fma_f32 v72, v72, s56, -v148
	v_exp_f32_e32 v72, v72
	v_fma_f32 v73, v73, s56, -v148
	v_exp_f32_e32 v73, v73
	v_mfma_f32_32x32x16_bf16 v[34:49], v[208:211], v[248:251], v[34:49]
	v_add_f32_e32 v252, v252, v66
	v_add_f32_e32 v253, v253, v67
	v_add_f32_e32 v252, v252, v68
	v_add_f32_e32 v253, v253, v69
	v_cvt_pk_bf16_f32 v212, v66, v67
	v_cvt_pk_bf16_f32 v213, v68, v69
	v_add_f32_e32 v252, v252, v70
	v_mfma_f32_32x32x16_bf16 v[18:33], v[208:211], v[84:87], v[18:33]
	v_add_f32_e32 v253, v253, v71
	v_add_f32_e32 v252, v252, v72
	v_add_f32_e32 v253, v253, v73
	v_cvt_pk_bf16_f32 v214, v70, v71
	v_cvt_pk_bf16_f32 v215, v72, v73
	ds_read_b64_tr_b16 v[240:241], v230 offset:12288
	ds_read_b64_tr_b16 v[242:243], v230 offset:14336
	ds_read_b64_tr_b16 v[244:245], v230 offset:12800
	ds_read_b64_tr_b16 v[246:247], v230 offset:14848
	ds_read_b64_tr_b16 v[248:249], v230 offset:13312
	ds_read_b64_tr_b16 v[250:251], v230 offset:15360
	ds_read_b64_tr_b16 v[84:85], v230 offset:13824
	ds_read_b64_tr_b16 v[86:87], v230 offset:15872
	s_mul_i32 s22, s17, 0x6000
	s_add_i32 s22, s20, s22
	s_add_i32 s23, s22, 0xe000
	s_add_i32 s24, s22, 0x10000
	s_add_i32 s22, s22, 0xc000
	s_lshl_b32 s25, s17, 14
	s_add_i32 s25, s20, s25
	s_add_i32 s26, s25, 0x2000
	s_cmp_lt_u32 s21, 30
	s_waitcnt lgkmcnt(8)
	v_mfma_f32_32x32x16_bf16 v[2:17], v[212:215], v[160:163], v[2:17]
	v_fma_f32 v74, v74, s56, -v148
	v_exp_f32_e32 v74, v74
	v_fma_f32 v75, v75, s56, -v148
	v_exp_f32_e32 v75, v75
	v_fma_f32 v76, v76, s56, -v148
	v_exp_f32_e32 v76, v76
	v_fma_f32 v77, v77, s56, -v148
	v_exp_f32_e32 v77, v77
	v_mfma_f32_32x32x16_bf16 v[50:65], v[212:215], v[164:167], v[50:65]
	v_fma_f32 v78, v78, s56, -v148
	v_exp_f32_e32 v78, v78
	v_fma_f32 v79, v79, s56, -v148
	v_exp_f32_e32 v79, v79
	v_fma_f32 v80, v80, s56, -v148
	v_exp_f32_e32 v80, v80
	v_fma_f32 v81, v81, s56, -v148
	v_exp_f32_e32 v81, v81
	v_mfma_f32_32x32x16_bf16 v[34:49], v[212:215], v[168:171], v[34:49]
	v_add_f32_e32 v252, v252, v74
	v_add_f32_e32 v253, v253, v75
	v_add_f32_e32 v252, v252, v76
	v_add_f32_e32 v253, v253, v77
	v_cvt_pk_bf16_f32 v236, v74, v75
	v_cvt_pk_bf16_f32 v237, v76, v77
	v_add_f32_e32 v252, v252, v78
	v_mfma_f32_32x32x16_bf16 v[18:33], v[212:215], v[172:175], v[18:33]
	v_add_f32_e32 v253, v253, v79
	v_add_f32_e32 v252, v252, v80
	v_add_f32_e32 v253, v253, v81
	v_cvt_pk_bf16_f32 v238, v78, v79
	v_cvt_pk_bf16_f32 v239, v80, v81
	s_cbranch_scc0 .Lmla_pd_0
	v_lshl_add_u64 v[66:67], s[2:3], 0, v[158:159]
	s_mov_b32 m0, s22
	s_nop 0
	global_load_lds_dwordx4 v[66:67], off
; #define ATT_SBAR() __builtin_amdgcn_sched_barrier(0)
; #define ATT_BAR() do { asm volatile("s_waitcnt lgkmcnt(0)" ::: "memory"); __builtin_amdgcn_s_barrier(); asm volatile("" ::: "memory"); } while (0)
; template <int MODE>
; __device__ __forceinline__ void attn_unit(unsigned char* ws_, const float* rpb, const float* sink, int l, int h, int qb, int kvq, unsigned char* lds_g) {
;     ...
;     ATT_SBAR();
;     if (j + 2 < T1) ATT_DMA(j + 2, bn);
;     if (j + 2 < T1) asm volatile("s_waitcnt vmcnt(%0)" :: "n"(NCH + 2) : "memory"); else asm volatile("s_waitcnt vmcnt(0)" ::: "memory");
;     ATT_BAR();
.Lmla_pd_0:
	s_waitcnt lgkmcnt(0)
	s_nop 0
	v_mfma_f32_32x32x16_bf16 v[2:17], v[236:239], v[240:243], v[2:17]
	v_add_f32_e32 v252, v252, v253
	s_cbranch_scc0 .Lmla_pd_1
	v_lshl_add_u64 v[66:67], s[2:3], 0, v[156:157]
	s_mov_b32 m0, s23
	s_nop 0
	global_load_lds_dwordx4 v[66:67], off
.Lmla_pd_1:
	v_mfma_f32_32x32x16_bf16 v[50:65], v[236:239], v[244:247], v[50:65]
	v_fmac_f32_e32 v252, v202, v203
	s_cbranch_scc0 .Lmla_pd_2
	v_lshl_add_u64 v[66:67], s[2:3], 0, v[154:155]
	s_mov_b32 m0, s24
	s_nop 0
	global_load_lds_dwordx4 v[66:67], off
.Lmla_pd_2:
	v_mfma_f32_32x32x16_bf16 v[34:49], v[236:239], v[248:251], v[34:49]
	v_mov_b32_e32 v202, v252
	s_cbranch_scc0 .Lmla_pd_3
	v_lshl_add_u64 v[66:67], s[2:3], 0, v[152:153]
	s_mov_b32 m0, s25
	s_nop 0
	global_load_lds_dwordx4 v[66:67], off
.Lmla_pd_3:
	v_mfma_f32_32x32x16_bf16 v[18:33], v[236:239], v[84:87], v[18:33]
	s_cbranch_scc0 .Lmla_pd_4
	v_lshl_add_u64 v[66:67], s[2:3], 0, v[150:151]
	s_mov_b32 m0, s26
	s_nop 0
	global_load_lds_dwordx4 v[66:67], off
.Lmla_pd_4:
.LBB0_873:
	s_cmp_lt_u32 s21, 30
	s_cbranch_scc1 .Lmla_w5
	s_waitcnt vmcnt(0)
	s_branch .LBB0_865
.Lmla_w5:
	s_waitcnt vmcnt(5)
	s_branch .LBB0_865
